# byte-phase experiment: whole instruction stream shifted by 32 bytes (eight s_nop 0 at entry) relative to the final candidate
# speedup vs baseline: 1.0109x; 1.0035x over previous
_Z10hybrid_fwd4Args:
	s_nop 0
	s_nop 0
	s_nop 0
	s_nop 0
	s_nop 0
	s_nop 0
	s_nop 0
	s_nop 0
	s_load_dwordx2 s[80:81], s[0:1], 0x80
	s_load_dwordx2 s[86:87], s[0:1], 0x90
	s_mov_b32 s93, s2
	s_add_u32 s2, s0, 0x90
	s_addc_u32 s3, s1, 0
	v_and_b32_e32 v212, 0x3ff, v0
	s_waitcnt lgkmcnt(0)
	s_and_b32 s4, s86, 7
	v_readfirstlane_b32 s85, v212
	s_cmp_lg_u32 s4, 0
	s_mov_b32 s84, s93
	s_cbranch_scc1 .LBB0_2
	s_ashr_i32 s5, s93, 31
	s_lshr_b32 s5, s5, 29
	s_add_i32 s5, s93, s5
	s_and_b32 s6, s5, -8
	s_ashr_i32 s4, s86, 3
	s_sub_i32 s6, s93, s6
	s_mul_i32 s4, s4, s6
	s_ashr_i32 s5, s5, 3
	s_add_i32 s84, s4, s5
